# v31_upw
# speedup vs baseline: 1.0045x; 1.0045x over previous
; #define LAS __attribute__((address_space(3)))
; #define LDS_WAIT() asm volatile("s_waitcnt lgkmcnt(0)" ::: "memory")
;     __device__ __forceinline__ int xidx(int ai, int w_r, int wc, int rsel, int fq, int bj, int n) const { return (((((ai * 2 + w_r) * 4 + wc) * 2 + rsel) * 4 + fq) * 4 + bj * 2 + n) * 16; }
;     __device__ __forceinline__ void operator()(AccT& acc, const Unit& u, int wr, int wc, int fr, int fq) const {
;     ...
;         if (fr >= 14) {
; #pragma unroll
;             for (int ai = 0; ai < 2; ++ai)
; #pragma unroll
;                 for (int bj = 0; bj < 2; ++bj)
; #pragma unroll
;                     for (int n = 0; n < 2; ++n) *(LAS f32x4*)(xl + xidx(ai, wr, wc, fr - 14, fq, bj, n)) = acc[ai][bj][3][n];
;             if (wr == 1) {
; #pragma unroll
;                 for (int bj = 0; bj < 2; ++bj)
; #pragma unroll
;                     for (int n = 0; n < 2; ++n) *(f32x4*)(HB + (size_t)(u.pm * 4 + fr - 14) * FF2 + u.pn * 256 + bj * 128 + lcol + 4 * n) = acc[1][bj][3][n]; }
;         }
;         if (wr == 0 && fr < 2) {
; #pragma unroll
;             for (int bj = 0; bj < 2; ++bj)
; #pragma unroll
;                 for (int n = 0; n < 2; ++n) *(f32x4*)(HB + (size_t)(u.pm * 4 + 2 + fr) * FF2 + u.pn * 256 + bj * 128 + lcol + 4 * n) = acc[0][bj][0][n]; }
;         LDS_WAIT(); __builtin_amdgcn_s_barrier();
;         u32x2 pend[2][4];
; #pragma unroll
;         for (int n = 0; n < 2; ++n) {
;             const int cg = u.pn * 128 + lcol + 4 * n;
;             f32x4 wgt[2][3], bia[2];
; #pragma unroll
;             for (int bj = 0; bj < 2; ++bj) { const int ch = cg + bj * FF; bia[bj] = *(const f32x4*)(cb + ch);
; #pragma unroll
;                 for (int k = 0; k < 3; ++k) wgt[bj][k] = *(const f32x4*)(cw + (size_t)k * FF2 + ch); }
.LBB0_781:
	v_mov_b32_e32 v108, v254
	v_cndmask_b32_e64 v118, 0, 1, s[26:27]
	v_and_b32_e32 v199, 15, v108
	v_bfe_u32 v108, v108, 4, 2
	v_lshl_or_b32 v109, v108, 3, s77
	v_cmp_lt_u32_e64 s[6:7], 13, v199
	v_lshl_or_b32 v108, v199, 2, v108
	v_cmp_ne_u32_e64 s[4:5], 1, v118
	v_lshl_or_b32 v186, s3, 7, v109
	v_ashrrev_i32_e32 v187, 31, v186
	v_lshlrev_b64 v[122:123], 2, v[186:187]
	v_lshl_add_u64 v[188:189], s[28:29], 0, v[122:123]
	v_lshl_add_u64 v[190:191], s[30:31], 0, v[122:123]
	global_load_dwordx4 v[200:203], v[190:191], off offset:16
	global_load_dwordx4 v[118:121], v[190:191], off
	global_load_dwordx4 v[204:207], v[188:189], off offset:16
	global_load_dwordx4 v[142:145], v[188:189], off
	s_mov_b64 s[8:9], 0x15000
	v_lshl_add_u64 v[122:123], v[188:189], 0, s[8:9]
	global_load_dwordx4 v[208:211], v[122:123], off offset:2064
	global_load_dwordx4 v[146:149], v[122:123], off offset:2048
	s_mov_b64 s[8:9], 0x2b000
	v_lshl_add_u64 v[122:123], v[188:189], 0, s[8:9]
	global_load_dwordx4 v[212:215], v[122:123], off offset:16
	global_load_dwordx4 v[150:153], v[122:123], off
	s_mov_b64 s[8:9], 0xa000
	v_lshl_add_u64 v[122:123], v[190:191], 0, s[8:9]
	v_lshl_add_u64 v[130:131], v[188:189], 0, s[8:9]
	global_load_dwordx4 v[216:219], v[122:123], off offset:3088
	global_load_dwordx4 v[122:125], v[122:123], off offset:3072
	s_mov_b64 s[8:9], 0x20000
	v_lshl_add_u64 v[132:133], v[188:189], 0, s[8:9]
	s_mov_b64 s[8:9], 0x35000
	v_lshl_add_u64 v[134:135], v[188:189], 0, s[8:9]
	global_load_dwordx4 v[220:223], v[130:131], off offset:3088
	global_load_dwordx4 v[138:141], v[130:131], off offset:3072
	global_load_dwordx4 v[224:227], v[132:133], off offset:1040
	global_load_dwordx4 v[130:133], v[132:133], off offset:1024
	global_load_dwordx4 v[228:231], v[134:135], off offset:3088
	global_load_dwordx4 v[134:137], v[134:135], off offset:3072
	s_and_saveexec_b64 s[12:13], s[6:7]
	s_cbranch_execz .LBB0_784
	v_add_u32_e32 v232, s85, v108
	v_lshl_add_u32 v232, v232, 6, 0
	v_add_u32_e32 v232, 0x1f200, v232
	s_and_b64 vcc, exec, s[4:5]
	ds_write_b128 v232, v[110:113]
	ds_write_b128 v232, v[36:39] offset:16
	ds_write_b128 v232, v[96:99] offset:32
	ds_write_b128 v232, v[32:35] offset:48
	ds_write_b128 v232, v[72:75] offset:4096
	ds_write_b128 v232, v[4:7] offset:4112
	ds_write_b128 v232, v[64:67] offset:4128
	ds_write_b128 v232, v[0:3] offset:4144
	s_cbranch_vccnz .LBB0_784
	s_lshl_b32 s8, s50, 2
	v_add3_u32 v234, s8, -14, v199
	s_lshl_b32 s8, s3, 8
	v_mov_b64_e32 v[232:233], s[38:39]
	s_ashr_i32 s9, s8, 31
	v_mad_i64_i32 v[232:233], s[16:17], v234, s93, v[232:233]
	v_lshl_add_u64 v[232:233], s[8:9], 2, v[232:233]
	v_lshlrev_b32_e32 v184, 2, v109
	v_lshl_add_u64 v[232:233], v[232:233], 0, v[184:185]
	global_store_dwordx4 v[232:233], v[72:75], off
	global_store_dwordx4 v[232:233], v[4:7], off offset:16
	global_store_dwordx4 v[232:233], v[64:67], off offset:512
	global_store_dwordx4 v[232:233], v[0:3], off offset:528
.LBB0_784:
	s_or_b64 exec, exec, s[12:13]
	v_cmp_gt_u32_e32 vcc, 2, v199
	s_and_b64 s[8:9], s[40:41], vcc
	s_and_saveexec_b64 s[12:13], s[8:9]
	s_cbranch_execz .LBB0_786
	s_lshl_b32 s8, s50, 2
	v_or3_b32 v234, v199, s8, 2
	s_lshl_b32 s8, s3, 8
	v_mov_b64_e32 v[232:233], s[38:39]
	s_ashr_i32 s9, s8, 31
	v_mad_i64_i32 v[232:233], s[16:17], v234, s93, v[232:233]
	v_lshl_add_u64 v[232:233], s[8:9], 2, v[232:233]
	v_lshlrev_b32_e32 v184, 2, v109
	v_lshl_add_u64 v[232:233], v[232:233], 0, v[184:185]
	global_store_dwordx4 v[232:233], v[158:161], off
	global_store_dwordx4 v[232:233], v[60:63], off offset:16
	global_store_dwordx4 v[232:233], v[104:107], off offset:512
	global_store_dwordx4 v[232:233], v[56:59], off offset:528
.LBB0_786:
	s_or_b64 exec, exec, s[12:13]
	s_waitcnt lgkmcnt(0)
	s_barrier
	v_add_u32_e32 v163, 0x3fffffc8, v108
	s_and_b64 s[12:13], s[26:27], s[6:7]
	v_mov_b32_e32 v162, 0
	v_lshl_add_u32 v184, v163, 6, s90
	v_mov_b32_e32 v164, 0
	v_mov_b32_e32 v165, 0
	v_mov_b32_e32 v166, 0
	v_mov_b32_e32 v167, 0
	v_mov_b32_e32 v168, 0
	v_mov_b32_e32 v169, 0
	v_mov_b32_e32 v170, 0
	v_mov_b32_e32 v171, 0
	s_and_saveexec_b64 s[16:17], s[12:13]
	s_cbranch_execz .LBB0_788
	ds_read_b128 v[168:171], v184
	ds_read_b128 v[164:167], v184 offset:32
.LBB0_788:
	s_or_b64 exec, exec, s[16:17]
	s_waitcnt lgkmcnt(0)
	v_mov_b32_dpp v109, v168 row_ror:2 row_mask:0xf bank_mask:0xf
	v_mov_b32_dpp v108, v168 row_ror:1 row_mask:0xf bank_mask:0xf
	v_mov_b32_dpp v109, v158 row_shr:2 row_mask:0xf bank_mask:0xf
	v_mov_b32_dpp v108, v158 row_shr:1 row_mask:0xf bank_mask:0xf
	s_and_b64 s[16:17], s[26:27], s[40:41]
	s_cbranch_scc1 .Lupc_w8
	s_or_b64 s[16:17], s[26:27], s[40:41]
	s_cbranch_scc1 .Lupc_w4
	s_waitcnt vmcnt(0)
	s_branch .Lupc_wd
.Lupc_w8:
	s_waitcnt vmcnt(8)
	s_branch .Lupc_wd
.Lupc_w4:
	s_waitcnt vmcnt(4)
; __device__ __forceinline__ unsigned cvt_pk_bf16(float lo, float hi) { unsigned r; asm volatile("v_cvt_pk_bf16_f32 %0, %1, %2" : "=v"(r) : "v"(lo), "v"(hi)); return r; }
; __device__ __forceinline__ float gelu_t(float x) { const float u = 1.5957691216f * (x + 0.044715f * x * x * x); return x * sigm(u); }
; __device__ __forceinline__ float dpp_shr1(float old, float src) { return __int_as_float(__builtin_amdgcn_update_dpp(__float_as_int(old), __float_as_int(src), 0x111, 0xf, 0xf, false)); }
; __device__ __forceinline__ float dpp_shr2(float old, float src) { return __int_as_float(__builtin_amdgcn_update_dpp(__float_as_int(old), __float_as_int(src), 0x112, 0xf, 0xf, false)); }
; __device__ __forceinline__ float dpp_ror1(float src) { return __int_as_float(__builtin_amdgcn_update_dpp(0, __float_as_int(src), 0x121, 0xf, 0xf, false)); }
; __device__ __forceinline__ float dpp_ror2(float src) { return __int_as_float(__builtin_amdgcn_update_dpp(0, __float_as_int(src), 0x122, 0xf, 0xf, false)); }
;     __device__ __forceinline__ void operator()(AccT& acc, const Unit& u, int wr, int wc, int fr, int fq) const {
;     ...
; #pragma unroll
;                 for (int m = 0; m < 4; ++m) {
;                     f32x4 c2[2];
; #pragma unroll
;                     for (int bj = 0; bj < 2; ++bj) { const f32x4 cur = acc[ai][bj][m][n]; const f32x4 pv = (m == 0) ? hv[bj] : acc[ai][bj][m == 0 ? 0 : m - 1][n];
; #pragma unroll
;                         for (int j = 0; j < 4; ++j) { const float p1 = dpp_shr1(dpp_ror1(pv[j]), cur[j]), p2 = dpp_shr2(dpp_ror2(pv[j]), cur[j]);
;                             c2[bj][j] = bia[bj][j] + wgt[bj][0][j] * p2 + wgt[bj][1][j] * p1 + wgt[bj][2][j] * cur[j]; } }
;                     u32x2 w; w.x = cvt_pk_bf16(gelu_t(c2[0][0]) * c2[1][0], gelu_t(c2[0][1]) * c2[1][1]); w.y = cvt_pk_bf16(gelu_t(c2[0][2]) * c2[1][2], gelu_t(c2[0][3]) * c2[1][3]);
;                     if (n == 0) pend[ai][m] = w;
.Lupc_wd:
	v_fma_f32 v109, v142, v109, v118
	v_fmac_f32_e32 v109, v146, v108
	v_mov_b32_dpp v168, v169 row_ror:2 row_mask:0xf bank_mask:0xf
	v_fmac_f32_e32 v109, v158, v150
	v_mov_b32_dpp v108, v169 row_ror:1 row_mask:0xf bank_mask:0xf
	v_mov_b32_dpp v168, v159 row_shr:2 row_mask:0xf bank_mask:0xf
	v_fma_f32 v168, v143, v168, v119
	v_mov_b32_dpp v108, v159 row_shr:1 row_mask:0xf bank_mask:0xf
	v_fmac_f32_e32 v168, v147, v108
	v_mov_b32_dpp v169, v170 row_ror:2 row_mask:0xf bank_mask:0xf
	v_fmac_f32_e32 v168, v159, v151
	v_mov_b32_dpp v108, v170 row_ror:1 row_mask:0xf bank_mask:0xf
	v_mov_b32_dpp v169, v160 row_shr:2 row_mask:0xf bank_mask:0xf
	v_fma_f32 v169, v144, v169, v120
	v_mov_b32_dpp v108, v160 row_shr:1 row_mask:0xf bank_mask:0xf
	v_fmac_f32_e32 v169, v148, v108
	v_mov_b32_dpp v170, v171 row_ror:2 row_mask:0xf bank_mask:0xf
	v_mul_f32_e32 v172, 0x3d372713, v168
	v_mov_b32_dpp v108, v171 row_ror:1 row_mask:0xf bank_mask:0xf
	v_mov_b32_dpp v170, v161 row_shr:2 row_mask:0xf bank_mask:0xf
	v_mov_b32_dpp v108, v161 row_shr:1 row_mask:0xf bank_mask:0xf
	v_fma_f32 v170, v145, v170, v121
	v_mov_b32_dpp v171, v164 row_ror:2 row_mask:0xf bank_mask:0xf
	v_fmac_f32_e32 v170, v149, v108
	v_mov_b32_dpp v171, v104 row_shr:2 row_mask:0xf bank_mask:0xf
	v_mul_f32_e32 v172, v168, v172
	v_mov_b32_dpp v108, v164 row_ror:1 row_mask:0xf bank_mask:0xf
	v_fma_f32 v164, v138, v171, v122
	v_mov_b32_dpp v108, v104 row_shr:1 row_mask:0xf bank_mask:0xf
	v_fmac_f32_e32 v164, v130, v108
	v_mov_b32_dpp v171, v165 row_ror:2 row_mask:0xf bank_mask:0xf
	v_fma_f32 v172, v168, v172, v168
	v_mov_b32_dpp v171, v105 row_shr:2 row_mask:0xf bank_mask:0xf
	v_mov_b32_dpp v108, v165 row_ror:1 row_mask:0xf bank_mask:0xf
	v_fma_f32 v165, v139, v171, v123
	v_mov_b32_dpp v108, v105 row_shr:1 row_mask:0xf bank_mask:0xf
	v_fmac_f32_e32 v165, v131, v108
	v_mov_b32_dpp v171, v166 row_ror:2 row_mask:0xf bank_mask:0xf
	v_mul_f32_e32 v172, 0x3fcc422a, v172
	v_mov_b32_dpp v171, v106 row_shr:2 row_mask:0xf bank_mask:0xf
	v_mov_b32_dpp v108, v166 row_ror:1 row_mask:0xf bank_mask:0xf
	v_fma_f32 v166, v140, v171, v124
	v_mov_b32_dpp v108, v106 row_shr:1 row_mask:0xf bank_mask:0xf
	v_fmac_f32_e32 v166, v132, v108
	v_mov_b32_dpp v171, v167 row_ror:2 row_mask:0xf bank_mask:0xf
	v_mul_f32_e32 v172, 0xbfb8aa3b, v172
	v_mov_b32_dpp v171, v107 row_shr:2 row_mask:0xf bank_mask:0xf
	v_mov_b32_dpp v108, v167 row_ror:1 row_mask:0xf bank_mask:0xf
	v_fma_f32 v167, v141, v171, v125
	v_mul_f32_e32 v171, 0x3d372713, v109
	v_mul_f32_e32 v171, v109, v171
	v_fma_f32 v171, v109, v171, v109
	v_mul_f32_e32 v171, 0x3fcc422a, v171
	v_mul_f32_e32 v171, 0xbfb8aa3b, v171
	v_exp_f32_e32 v171, v171
	v_exp_f32_e32 v172, v172
	v_mov_b32_dpp v108, v107 row_shr:1 row_mask:0xf bank_mask:0xf
	v_fmac_f32_e32 v167, v133, v108
	v_add_f32_e32 v108, 1.0, v171
	v_rcp_f32_e32 v108, v108
	v_add_f32_e32 v171, 1.0, v172
	v_rcp_f32_e32 v171, v171
	v_fmac_f32_e32 v169, v160, v152
	v_fmac_f32_e32 v170, v161, v153
	v_fmac_f32_e32 v164, v104, v134
	v_mul_f32_e32 v108, v109, v108
	v_mul_f32_e32 v108, v108, v164
	v_mul_f32_e32 v109, v168, v171
	v_mul_f32_e32 v164, 0x3d372713, v169
	v_mul_f32_e32 v168, 0x3d372713, v170
	v_mul_f32_e32 v164, v169, v164
	v_mul_f32_e32 v168, v170, v168
	v_fma_f32 v164, v169, v164, v169
	v_fma_f32 v168, v170, v168, v170
	v_mul_f32_e32 v164, 0x3fcc422a, v164
	v_mul_f32_e32 v168, 0x3fcc422a, v168
	v_mul_f32_e32 v164, 0xbfb8aa3b, v164
	v_mul_f32_e32 v168, 0xbfb8aa3b, v168
	v_exp_f32_e32 v164, v164
	v_exp_f32_e32 v168, v168
	v_fmac_f32_e32 v165, v105, v135
	v_mul_f32_e32 v109, v109, v165
	v_add_f32_e32 v164, 1.0, v164
	v_add_f32_e32 v165, 1.0, v168
	v_rcp_f32_e32 v164, v164
	v_rcp_f32_e32 v165, v165
	v_fmac_f32_e32 v166, v106, v136
	v_fmac_f32_e32 v167, v107, v137
	v_cvt_pk_bf16_f32 v108, v108, v109
	v_mul_f32_e32 v109, v169, v164
	v_mul_f32_e32 v164, v170, v165
	v_mul_f32_e32 v109, v109, v166
	v_mul_f32_e32 v164, v164, v167
	v_cvt_pk_bf16_f32 v109, v109, v164
	s_nop 0
	v_mov_b32_dpp v165, v158 row_ror:2 row_mask:0xf bank_mask:0xf
	v_mov_b32_dpp v164, v158 row_ror:1 row_mask:0xf bank_mask:0xf
	s_nop 0
	v_mov_b32_dpp v165, v154 row_shr:2 row_mask:0xf bank_mask:0xf
	v_mov_b32_dpp v164, v154 row_shr:1 row_mask:0xf bank_mask:0xf
	v_fma_f32 v158, v142, v165, v118
	v_fmac_f32_e32 v158, v146, v164
	v_mov_b32_dpp v165, v159 row_ror:2 row_mask:0xf bank_mask:0xf
	v_fmac_f32_e32 v158, v154, v150
	v_mov_b32_dpp v164, v159 row_ror:1 row_mask:0xf bank_mask:0xf
	v_mov_b32_dpp v165, v155 row_shr:2 row_mask:0xf bank_mask:0xf
	v_fma_f32 v159, v143, v165, v119
	v_mov_b32_dpp v164, v155 row_shr:1 row_mask:0xf bank_mask:0xf
	v_fmac_f32_e32 v159, v147, v164
	v_mov_b32_dpp v165, v160 row_ror:2 row_mask:0xf bank_mask:0xf
	v_fmac_f32_e32 v159, v155, v151
	v_mov_b32_dpp v164, v160 row_ror:1 row_mask:0xf bank_mask:0xf
	v_mov_b32_dpp v165, v156 row_shr:2 row_mask:0xf bank_mask:0xf
	v_fma_f32 v160, v144, v165, v120
	v_mov_b32_dpp v164, v156 row_shr:1 row_mask:0xf bank_mask:0xf
	v_fmac_f32_e32 v160, v148, v164
	v_mov_b32_dpp v165, v161 row_ror:2 row_mask:0xf bank_mask:0xf
	v_mul_f32_e32 v166, 0x3d372713, v159
	v_mov_b32_dpp v164, v161 row_ror:1 row_mask:0xf bank_mask:0xf
	v_mov_b32_dpp v165, v157 row_shr:2 row_mask:0xf bank_mask:0xf
	v_fma_f32 v161, v145, v165, v121
	v_mov_b32_dpp v164, v157 row_shr:1 row_mask:0xf bank_mask:0xf
	v_fmac_f32_e32 v161, v149, v164
	v_mov_b32_dpp v165, v104 row_ror:2 row_mask:0xf bank_mask:0xf
	v_mul_f32_e32 v166, v159, v166
	v_mov_b32_dpp v164, v104 row_ror:1 row_mask:0xf bank_mask:0xf
	v_mov_b32_dpp v165, v126 row_shr:2 row_mask:0xf bank_mask:0xf
	v_fma_f32 v104, v138, v165, v122
	v_mov_b32_dpp v164, v126 row_shr:1 row_mask:0xf bank_mask:0xf
; __device__ __forceinline__ unsigned cvt_pk_bf16(float lo, float hi) { unsigned r; asm volatile("v_cvt_pk_bf16_f32 %0, %1, %2" : "=v"(r) : "v"(lo), "v"(hi)); return r; }
; __device__ __forceinline__ float gelu_t(float x) { const float u = 1.5957691216f * (x + 0.044715f * x * x * x); return x * sigm(u); }
; __device__ __forceinline__ float dpp_shr1(float old, float src) { return __int_as_float(__builtin_amdgcn_update_dpp(__float_as_int(old), __float_as_int(src), 0x111, 0xf, 0xf, false)); }
; __device__ __forceinline__ float dpp_shr2(float old, float src) { return __int_as_float(__builtin_amdgcn_update_dpp(__float_as_int(old), __float_as_int(src), 0x112, 0xf, 0xf, false)); }
; __device__ __forceinline__ float dpp_ror1(float src) { return __int_as_float(__builtin_amdgcn_update_dpp(0, __float_as_int(src), 0x121, 0xf, 0xf, false)); }
; __device__ __forceinline__ float dpp_ror2(float src) { return __int_as_float(__builtin_amdgcn_update_dpp(0, __float_as_int(src), 0x122, 0xf, 0xf, false)); }
;     __device__ __forceinline__ void operator()(AccT& acc, const Unit& u, int wr, int wc, int fr, int fq) const {
;     ...
;                 for (int m = 0; m < 4; ++m) {
;                     f32x4 c2[2];
; #pragma unroll
;                     for (int bj = 0; bj < 2; ++bj) { const f32x4 cur = acc[ai][bj][m][n]; const f32x4 pv = (m == 0) ? hv[bj] : acc[ai][bj][m == 0 ? 0 : m - 1][n];
; #pragma unroll
;                         for (int j = 0; j < 4; ++j) { const float p1 = dpp_shr1(dpp_ror1(pv[j]), cur[j]), p2 = dpp_shr2(dpp_ror2(pv[j]), cur[j]);
;                             c2[bj][j] = bia[bj][j] + wgt[bj][0][j] * p2 + wgt[bj][1][j] * p1 + wgt[bj][2][j] * cur[j]; } }
;                     u32x2 w; w.x = cvt_pk_bf16(gelu_t(c2[0][0]) * c2[1][0], gelu_t(c2[0][1]) * c2[1][1]); w.y = cvt_pk_bf16(gelu_t(c2[0][2]) * c2[1][2], gelu_t(c2[0][3]) * c2[1][3]);
;                     if (n == 0) pend[ai][m] = w;
	v_fmac_f32_e32 v104, v130, v164
	v_mov_b32_dpp v165, v105 row_ror:2 row_mask:0xf bank_mask:0xf
	v_fma_f32 v166, v159, v166, v159
	v_mov_b32_dpp v164, v105 row_ror:1 row_mask:0xf bank_mask:0xf
	v_mov_b32_dpp v165, v127 row_shr:2 row_mask:0xf bank_mask:0xf
	v_fma_f32 v105, v139, v165, v123
	v_mov_b32_dpp v164, v127 row_shr:1 row_mask:0xf bank_mask:0xf
	v_fmac_f32_e32 v105, v131, v164
	v_mov_b32_dpp v165, v106 row_ror:2 row_mask:0xf bank_mask:0xf
	v_mul_f32_e32 v166, 0x3fcc422a, v166
	v_mov_b32_dpp v164, v106 row_ror:1 row_mask:0xf bank_mask:0xf
	v_mov_b32_dpp v165, v128 row_shr:2 row_mask:0xf bank_mask:0xf
	v_fma_f32 v165, v140, v165, v124
	v_mov_b32_dpp v164, v128 row_shr:1 row_mask:0xf bank_mask:0xf
	v_fmac_f32_e32 v165, v132, v164
	v_mul_f32_e32 v166, 0xbfb8aa3b, v166
	v_mov_b32_dpp v164, v107 row_ror:2 row_mask:0xf bank_mask:0xf
	v_mov_b32_dpp v106, v107 row_ror:1 row_mask:0xf bank_mask:0xf
	v_exp_f32_e32 v166, v166
	v_mov_b32_dpp v164, v129 row_shr:2 row_mask:0xf bank_mask:0xf
	v_fma_f32 v107, v141, v164, v125
	v_mul_f32_e32 v164, 0x3d372713, v158
	v_mul_f32_e32 v164, v158, v164
	v_fma_f32 v164, v158, v164, v158
	v_mul_f32_e32 v164, 0x3fcc422a, v164
	v_mul_f32_e32 v164, 0xbfb8aa3b, v164
	v_exp_f32_e32 v164, v164
	v_mov_b32_dpp v106, v129 row_shr:1 row_mask:0xf bank_mask:0xf
	v_fmac_f32_e32 v107, v133, v106
	v_fmac_f32_e32 v160, v156, v152
	v_add_f32_e32 v106, 1.0, v164
	v_rcp_f32_e32 v106, v106
	v_add_f32_e32 v164, 1.0, v166
	v_rcp_f32_e32 v164, v164
	v_fmac_f32_e32 v161, v157, v153
	v_fmac_f32_e32 v104, v126, v134
	v_mul_f32_e32 v106, v158, v106
	v_mul_f32_e32 v158, 0x3d372713, v160
	v_mul_f32_e32 v104, v106, v104
	v_mul_f32_e32 v106, v159, v164
	v_mul_f32_e32 v158, v160, v158
	v_mul_f32_e32 v159, 0x3d372713, v161
	v_fma_f32 v158, v160, v158, v160
	v_mul_f32_e32 v159, v161, v159
	v_mul_f32_e32 v158, 0x3fcc422a, v158
	v_fma_f32 v159, v161, v159, v161
	v_mul_f32_e32 v158, 0xbfb8aa3b, v158
	v_mul_f32_e32 v159, 0x3fcc422a, v159
	v_exp_f32_e32 v158, v158
	v_mul_f32_e32 v159, 0xbfb8aa3b, v159
	v_exp_f32_e32 v159, v159
	v_fmac_f32_e32 v105, v127, v135
	v_mul_f32_e32 v105, v106, v105
	v_add_f32_e32 v106, 1.0, v158
	v_rcp_f32_e32 v158, v106
	v_add_f32_e32 v106, 1.0, v159
	v_rcp_f32_e32 v159, v106
	v_fmac_f32_e32 v107, v129, v137
	v_cvt_pk_bf16_f32 v106, v104, v105
	v_fmac_f32_e32 v165, v128, v136
	v_mul_f32_e32 v105, v161, v159
	v_mul_f32_e32 v104, v160, v158
	v_mul_f32_e32 v105, v105, v107
	v_mul_f32_e32 v104, v104, v165
	v_cvt_pk_bf16_f32 v107, v104, v105
	v_mov_b32_e32 v164, 0
	v_mov_b32_dpp v105, v154 row_ror:2 row_mask:0xf bank_mask:0xf
	v_mov_b32_dpp v104, v154 row_ror:1 row_mask:0xf bank_mask:0xf
	v_mov_b32_dpp v105, v114 row_shr:2 row_mask:0xf bank_mask:0xf
	v_mov_b32_dpp v104, v114 row_shr:1 row_mask:0xf bank_mask:0xf
	v_fma_f32 v105, v142, v105, v118
	v_fmac_f32_e32 v105, v146, v104
	v_mov_b32_dpp v154, v155 row_ror:2 row_mask:0xf bank_mask:0xf
	v_fmac_f32_e32 v105, v114, v150
	v_mov_b32_dpp v104, v155 row_ror:1 row_mask:0xf bank_mask:0xf
	v_mov_b32_dpp v154, v115 row_shr:2 row_mask:0xf bank_mask:0xf
	v_fma_f32 v154, v143, v154, v119
	v_mov_b32_dpp v104, v115 row_shr:1 row_mask:0xf bank_mask:0xf
	v_fmac_f32_e32 v154, v147, v104
	v_mov_b32_dpp v155, v156 row_ror:2 row_mask:0xf bank_mask:0xf
	v_fmac_f32_e32 v154, v115, v151
	v_mov_b32_dpp v104, v156 row_ror:1 row_mask:0xf bank_mask:0xf
	v_mov_b32_dpp v155, v116 row_shr:2 row_mask:0xf bank_mask:0xf
	v_fma_f32 v155, v144, v155, v120
	v_mov_b32_dpp v104, v116 row_shr:1 row_mask:0xf bank_mask:0xf
	v_fmac_f32_e32 v155, v148, v104
	v_mov_b32_dpp v156, v157 row_ror:2 row_mask:0xf bank_mask:0xf
	v_mul_f32_e32 v158, 0x3d372713, v154
	v_mov_b32_dpp v104, v157 row_ror:1 row_mask:0xf bank_mask:0xf
	v_mov_b32_dpp v156, v117 row_shr:2 row_mask:0xf bank_mask:0xf
	v_mov_b32_dpp v104, v117 row_shr:1 row_mask:0xf bank_mask:0xf
	v_fma_f32 v156, v145, v156, v121
	v_mov_b32_dpp v157, v126 row_ror:2 row_mask:0xf bank_mask:0xf
	v_fmac_f32_e32 v156, v149, v104
	v_mov_b32_dpp v157, v100 row_shr:2 row_mask:0xf bank_mask:0xf
	v_mul_f32_e32 v158, v154, v158
	v_mov_b32_dpp v104, v126 row_ror:1 row_mask:0xf bank_mask:0xf
	v_fma_f32 v126, v138, v157, v122
	v_mov_b32_dpp v104, v100 row_shr:1 row_mask:0xf bank_mask:0xf
	v_fmac_f32_e32 v126, v130, v104
	v_mov_b32_dpp v157, v127 row_ror:2 row_mask:0xf bank_mask:0xf
	v_fma_f32 v158, v154, v158, v154
	v_mov_b32_dpp v157, v101 row_shr:2 row_mask:0xf bank_mask:0xf
	v_mov_b32_dpp v104, v127 row_ror:1 row_mask:0xf bank_mask:0xf
	v_fma_f32 v127, v139, v157, v123
	v_mov_b32_dpp v104, v101 row_shr:1 row_mask:0xf bank_mask:0xf
	v_fmac_f32_e32 v127, v131, v104
	v_mov_b32_dpp v157, v128 row_ror:2 row_mask:0xf bank_mask:0xf
	v_mul_f32_e32 v158, 0x3fcc422a, v158
	v_mov_b32_dpp v157, v102 row_shr:2 row_mask:0xf bank_mask:0xf
	v_mov_b32_dpp v104, v128 row_ror:1 row_mask:0xf bank_mask:0xf
	v_fma_f32 v128, v140, v157, v124
	v_mov_b32_dpp v104, v102 row_shr:1 row_mask:0xf bank_mask:0xf
	v_fmac_f32_e32 v128, v132, v104
	v_mov_b32_dpp v157, v129 row_ror:2 row_mask:0xf bank_mask:0xf
	v_mul_f32_e32 v158, 0xbfb8aa3b, v158
	v_mov_b32_dpp v157, v103 row_shr:2 row_mask:0xf bank_mask:0xf
	v_mov_b32_dpp v104, v129 row_ror:1 row_mask:0xf bank_mask:0xf
	v_fma_f32 v129, v141, v157, v125
	v_mul_f32_e32 v157, 0x3d372713, v105
	v_mul_f32_e32 v157, v105, v157
	v_fma_f32 v157, v105, v157, v105
	v_mul_f32_e32 v157, 0x3fcc422a, v157
	v_mul_f32_e32 v157, 0xbfb8aa3b, v157
	v_exp_f32_e32 v157, v157
	v_exp_f32_e32 v158, v158
	v_mov_b32_dpp v104, v103 row_shr:1 row_mask:0xf bank_mask:0xf
	v_fmac_f32_e32 v129, v133, v104
	v_add_f32_e32 v104, 1.0, v157
	v_rcp_f32_e32 v104, v104
; #define LAS __attribute__((address_space(3)))
; __device__ __forceinline__ unsigned cvt_pk_bf16(float lo, float hi) { unsigned r; asm volatile("v_cvt_pk_bf16_f32 %0, %1, %2" : "=v"(r) : "v"(lo), "v"(hi)); return r; }
; __device__ __forceinline__ float gelu_t(float x) { const float u = 1.5957691216f * (x + 0.044715f * x * x * x); return x * sigm(u); }
; __device__ __forceinline__ float dpp_shr1(float old, float src) { return __int_as_float(__builtin_amdgcn_update_dpp(__float_as_int(old), __float_as_int(src), 0x111, 0xf, 0xf, false)); }
; __device__ __forceinline__ float dpp_shr2(float old, float src) { return __int_as_float(__builtin_amdgcn_update_dpp(__float_as_int(old), __float_as_int(src), 0x112, 0xf, 0xf, false)); }
; __device__ __forceinline__ float dpp_ror1(float src) { return __int_as_float(__builtin_amdgcn_update_dpp(0, __float_as_int(src), 0x121, 0xf, 0xf, false)); }
; __device__ __forceinline__ float dpp_ror2(float src) { return __int_as_float(__builtin_amdgcn_update_dpp(0, __float_as_int(src), 0x122, 0xf, 0xf, false)); }
;     __device__ __forceinline__ int xidx(int ai, int w_r, int wc, int rsel, int fq, int bj, int n) const { return (((((ai * 2 + w_r) * 4 + wc) * 2 + rsel) * 4 + fq) * 4 + bj * 2 + n) * 16; }
;     __device__ __forceinline__ void operator()(AccT& acc, const Unit& u, int wr, int wc, int fr, int fq) const {
;     ...
;                 if (has_pred && fr >= 14) { hv[0] = *(const LAS f32x4*)(xl + xidx(pa, pw, wc, fr - 14, fq, 0, n)); hv[1] = *(const LAS f32x4*)(xl + xidx(pa, pw, wc, fr - 14, fq, 1, n)); }
; #pragma unroll
;                 for (int m = 0; m < 4; ++m) {
;                     f32x4 c2[2];
; #pragma unroll
;                     for (int bj = 0; bj < 2; ++bj) { const f32x4 cur = acc[ai][bj][m][n]; const f32x4 pv = (m == 0) ? hv[bj] : acc[ai][bj][m == 0 ? 0 : m - 1][n];
; #pragma unroll
;                         for (int j = 0; j < 4; ++j) { const float p1 = dpp_shr1(dpp_ror1(pv[j]), cur[j]), p2 = dpp_shr2(dpp_ror2(pv[j]), cur[j]);
;                             c2[bj][j] = bia[bj][j] + wgt[bj][0][j] * p2 + wgt[bj][1][j] * p1 + wgt[bj][2][j] * cur[j]; } }
;                     u32x2 w; w.x = cvt_pk_bf16(gelu_t(c2[0][0]) * c2[1][0], gelu_t(c2[0][1]) * c2[1][1]); w.y = cvt_pk_bf16(gelu_t(c2[0][2]) * c2[1][2], gelu_t(c2[0][3]) * c2[1][3]);
;                     if (n == 0) pend[ai][m] = w;
	v_add_f32_e32 v157, 1.0, v158
	v_rcp_f32_e32 v157, v157
	v_fmac_f32_e32 v155, v116, v152
	v_fmac_f32_e32 v156, v117, v153
	v_fmac_f32_e32 v126, v100, v134
	v_mul_f32_e32 v104, v105, v104
	v_mul_f32_e32 v104, v104, v126
	v_mul_f32_e32 v105, v154, v157
	v_mul_f32_e32 v126, 0x3d372713, v155
	v_mul_f32_e32 v154, 0x3d372713, v156
	v_mul_f32_e32 v126, v155, v126
	v_mul_f32_e32 v154, v156, v154
	v_fma_f32 v126, v155, v126, v155
	v_fma_f32 v154, v156, v154, v156
	v_mul_f32_e32 v126, 0x3fcc422a, v126
	v_mul_f32_e32 v154, 0x3fcc422a, v154
	v_mul_f32_e32 v126, 0xbfb8aa3b, v126
	v_mul_f32_e32 v154, 0xbfb8aa3b, v154
	v_exp_f32_e32 v126, v126
	v_exp_f32_e32 v154, v154
	v_fmac_f32_e32 v127, v101, v135
	v_mul_f32_e32 v105, v105, v127
	v_add_f32_e32 v126, 1.0, v126
	v_add_f32_e32 v127, 1.0, v154
	v_rcp_f32_e32 v126, v126
	v_rcp_f32_e32 v127, v127
	v_fmac_f32_e32 v128, v102, v136
	v_fmac_f32_e32 v129, v103, v137
	v_cvt_pk_bf16_f32 v104, v104, v105
	v_mul_f32_e32 v105, v155, v126
	v_mul_f32_e32 v126, v156, v127
	v_mul_f32_e32 v105, v105, v128
	v_mul_f32_e32 v126, v126, v129
	v_cvt_pk_bf16_f32 v105, v105, v126
	v_lshl_add_u32 v154, v163, 6, s91
	v_mov_b32_dpp v127, v114 row_ror:2 row_mask:0xf bank_mask:0xf
	v_mov_b32_dpp v126, v114 row_ror:1 row_mask:0xf bank_mask:0xf
	v_mov_b32_e32 v163, 0
	v_mov_b32_dpp v127, v110 row_shr:2 row_mask:0xf bank_mask:0xf
	v_mov_b32_dpp v126, v110 row_shr:1 row_mask:0xf bank_mask:0xf
	v_fma_f32 v114, v142, v127, v118
	v_fmac_f32_e32 v114, v146, v126
	v_fmac_f32_e32 v114, v110, v150
	v_mov_b32_dpp v126, v115 row_ror:2 row_mask:0xf bank_mask:0xf
	v_mov_b32_e32 v165, 0
	v_mov_b32_dpp v110, v115 row_ror:1 row_mask:0xf bank_mask:0xf
	v_mov_b32_dpp v126, v111 row_shr:2 row_mask:0xf bank_mask:0xf
	v_fma_f32 v115, v143, v126, v119
	v_mov_b32_dpp v110, v111 row_shr:1 row_mask:0xf bank_mask:0xf
	v_fmac_f32_e32 v115, v147, v110
	v_fmac_f32_e32 v115, v111, v151
	s_nop 0
	v_mov_b32_dpp v111, v116 row_ror:2 row_mask:0xf bank_mask:0xf
	v_mov_b32_dpp v110, v116 row_ror:1 row_mask:0xf bank_mask:0xf
	s_nop 0
	v_mov_b32_dpp v111, v112 row_shr:2 row_mask:0xf bank_mask:0xf
	v_mov_b32_dpp v110, v112 row_shr:1 row_mask:0xf bank_mask:0xf
	v_fma_f32 v111, v144, v111, v120
	v_fmac_f32_e32 v111, v148, v110
	v_fmac_f32_e32 v111, v112, v152
	s_nop 0
	v_mov_b32_dpp v112, v117 row_ror:2 row_mask:0xf bank_mask:0xf
	v_mov_b32_dpp v110, v117 row_ror:1 row_mask:0xf bank_mask:0xf
	s_nop 0
	v_mov_b32_dpp v112, v113 row_shr:2 row_mask:0xf bank_mask:0xf
	v_mov_b32_dpp v110, v113 row_shr:1 row_mask:0xf bank_mask:0xf
	v_fma_f32 v112, v145, v112, v121
	v_fmac_f32_e32 v112, v149, v110
	v_fmac_f32_e32 v112, v113, v153
	s_nop 0
	v_mov_b32_dpp v113, v100 row_ror:2 row_mask:0xf bank_mask:0xf
	v_mov_b32_dpp v110, v100 row_ror:1 row_mask:0xf bank_mask:0xf
	s_nop 0
	v_mov_b32_dpp v113, v96 row_shr:2 row_mask:0xf bank_mask:0xf
	v_mov_b32_dpp v110, v96 row_shr:1 row_mask:0xf bank_mask:0xf
	v_fma_f32 v100, v138, v113, v122
	v_fmac_f32_e32 v100, v130, v110
	v_fmac_f32_e32 v100, v96, v134
	v_mov_b32_dpp v110, v101 row_ror:2 row_mask:0xf bank_mask:0xf
	s_nop 0
	v_mov_b32_dpp v96, v101 row_ror:1 row_mask:0xf bank_mask:0xf
	v_mov_b32_dpp v110, v97 row_shr:2 row_mask:0xf bank_mask:0xf
	v_fma_f32 v101, v139, v110, v123
	v_mov_b32_dpp v96, v97 row_shr:1 row_mask:0xf bank_mask:0xf
	v_fmac_f32_e32 v101, v131, v96
	v_fmac_f32_e32 v101, v97, v135
	s_nop 0
	v_mov_b32_dpp v97, v102 row_ror:2 row_mask:0xf bank_mask:0xf
	v_mov_b32_dpp v96, v102 row_ror:1 row_mask:0xf bank_mask:0xf
	s_nop 0
	v_mov_b32_dpp v97, v98 row_shr:2 row_mask:0xf bank_mask:0xf
	v_mov_b32_dpp v96, v98 row_shr:1 row_mask:0xf bank_mask:0xf
	v_fma_f32 v97, v140, v97, v124
	v_fmac_f32_e32 v97, v132, v96
	v_fmac_f32_e32 v97, v98, v136
	s_nop 0
	v_mov_b32_dpp v98, v103 row_ror:2 row_mask:0xf bank_mask:0xf
	v_mov_b32_dpp v96, v103 row_ror:1 row_mask:0xf bank_mask:0xf
	v_mul_f32_e32 v103, 0x3d372713, v115
	v_mov_b32_dpp v98, v99 row_shr:2 row_mask:0xf bank_mask:0xf
	v_fma_f32 v102, v141, v98, v125
	v_mul_f32_e32 v98, 0x3d372713, v114
	v_mul_f32_e32 v98, v114, v98
	v_fma_f32 v98, v114, v98, v114
	v_mul_f32_e32 v98, 0x3fcc422a, v98
	v_mul_f32_e32 v98, 0xbfb8aa3b, v98
	v_exp_f32_e32 v98, v98
	v_mov_b32_dpp v96, v99 row_shr:1 row_mask:0xf bank_mask:0xf
	v_fmac_f32_e32 v102, v133, v96
	v_mul_f32_e32 v103, v115, v103
	v_add_f32_e32 v96, 1.0, v98
	v_rcp_f32_e32 v96, v96
	v_fma_f32 v103, v115, v103, v115
	v_fmac_f32_e32 v102, v99, v137
	v_mul_f32_e32 v99, 0x3d372713, v111
	v_mul_f32_e32 v96, v114, v96
	v_mul_f32_e32 v103, 0x3fcc422a, v103
	v_mul_f32_e32 v96, v96, v100
	v_mul_f32_e32 v99, v111, v99
	v_mul_f32_e32 v100, 0x3d372713, v112
	v_mul_f32_e32 v103, 0xbfb8aa3b, v103
	v_fma_f32 v99, v111, v99, v111
	v_mul_f32_e32 v100, v112, v100
	v_exp_f32_e32 v103, v103
	v_mul_f32_e32 v99, 0x3fcc422a, v99
	v_fma_f32 v100, v112, v100, v112
	v_mul_f32_e32 v99, 0xbfb8aa3b, v99
	v_mul_f32_e32 v100, 0x3fcc422a, v100
	v_exp_f32_e32 v99, v99
	v_mul_f32_e32 v100, 0xbfb8aa3b, v100
	v_exp_f32_e32 v100, v100
	v_add_f32_e32 v98, 1.0, v103
	v_rcp_f32_e32 v98, v98
	v_add_f32_e32 v99, 1.0, v99
	v_rcp_f32_e32 v99, v99
	v_add_f32_e32 v100, 1.0, v100
	v_rcp_f32_e32 v100, v100
	v_mul_f32_e32 v98, v115, v98
	v_mul_f32_e32 v98, v98, v101
	v_cvt_pk_bf16_f32 v98, v96, v98
	v_mul_f32_e32 v96, v111, v99
	v_mul_f32_e32 v96, v96, v97
	v_mul_f32_e32 v97, v112, v100
	v_mul_f32_e32 v97, v97, v102
	v_mov_b32_e32 v100, 0
	v_mov_b32_e32 v101, 0
	v_mov_b32_e32 v102, 0
	v_mov_b32_e32 v103, 0
	v_cvt_pk_bf16_f32 v99, v96, v97
	s_and_saveexec_b64 s[16:17], s[6:7]
	s_cbranch_execz .LBB0_790
	ds_read_b128 v[100:103], v154
	ds_read_b128 v[162:165], v154 offset:32

; __device__ __forceinline__ unsigned cvt_pk_bf16(float lo, float hi) { unsigned r; asm volatile("v_cvt_pk_bf16_f32 %0, %1, %2" : "=v"(r) : "v"(lo), "v"(hi)); return r; }
; __device__ __forceinline__ float gelu_t(float x) { const float u = 1.5957691216f * (x + 0.044715f * x * x * x); return x * sigm(u); }
; __device__ __forceinline__ float dpp_shr1(float old, float src) { return __int_as_float(__builtin_amdgcn_update_dpp(__float_as_int(old), __float_as_int(src), 0x111, 0xf, 0xf, false)); }
; __device__ __forceinline__ float dpp_shr2(float old, float src) { return __int_as_float(__builtin_amdgcn_update_dpp(__float_as_int(old), __float_as_int(src), 0x112, 0xf, 0xf, false)); }
; __device__ __forceinline__ float dpp_ror1(float src) { return __int_as_float(__builtin_amdgcn_update_dpp(0, __float_as_int(src), 0x121, 0xf, 0xf, false)); }
; __device__ __forceinline__ float dpp_ror2(float src) { return __int_as_float(__builtin_amdgcn_update_dpp(0, __float_as_int(src), 0x122, 0xf, 0xf, false)); }
;     __device__ __forceinline__ void operator()(AccT& acc, const Unit& u, int wr, int wc, int fr, int fq) const {
;     ...
;                 for (int m = 0; m < 4; ++m) {
;                     f32x4 c2[2];
; #pragma unroll
;                     for (int bj = 0; bj < 2; ++bj) { const f32x4 cur = acc[ai][bj][m][n]; const f32x4 pv = (m == 0) ? hv[bj] : acc[ai][bj][m == 0 ? 0 : m - 1][n];
; #pragma unroll
;                         for (int j = 0; j < 4; ++j) { const float p1 = dpp_shr1(dpp_ror1(pv[j]), cur[j]), p2 = dpp_shr2(dpp_ror2(pv[j]), cur[j]);
;                             c2[bj][j] = bia[bj][j] + wgt[bj][0][j] * p2 + wgt[bj][1][j] * p1 + wgt[bj][2][j] * cur[j]; } }
;                     u32x2 w; w.x = cvt_pk_bf16(gelu_t(c2[0][0]) * c2[1][0], gelu_t(c2[0][1]) * c2[1][1]); w.y = cvt_pk_bf16(gelu_t(c2[0][2]) * c2[1][2], gelu_t(c2[0][3]) * c2[1][3]);
;                     if (n == 0) pend[ai][m] = w;
;                     else { u32x4 w4; w4.x = pend[ai][m].x; w4.y = pend[ai][m].y; w4.z = w.x; w4.w = w.y;
;                         *(u32x4*)(F + (size_t)(t0 + ai * 128 + wr * 64 + m * 16 + fr) * FF + cg - 4) = w4; }
.LBB0_792:
	s_or_b64 exec, exec, s[16:17]
	s_waitcnt lgkmcnt(1)
	v_mov_b32_dpp v126, v122 row_ror:2 row_mask:0xf bank_mask:0xf
	s_waitcnt lgkmcnt(0)
	v_mov_b32_dpp v127, v118 row_ror:2 row_mask:0xf bank_mask:0xf
	v_mov_b32_dpp v82, v122 row_ror:1 row_mask:0xf bank_mask:0xf
	v_mov_b32_dpp v126, v60 row_shr:2 row_mask:0xf bank_mask:0xf
	v_mov_b32_dpp v128, v123 row_ror:1 row_mask:0xf bank_mask:0xf
	v_mov_b32_dpp v130, v123 row_ror:2 row_mask:0xf bank_mask:0xf
	v_mov_b32_dpp v83, v118 row_ror:1 row_mask:0xf bank_mask:0xf
	v_mov_b32_dpp v127, v56 row_shr:2 row_mask:0xf bank_mask:0xf
	v_mov_b32_e32 v78, v114
	v_mov_b32_e32 v79, v74
	v_mov_b32_e32 v122, v100
	v_mov_b32_e32 v123, v70
	v_mov_b32_dpp v82, v60 row_shr:1 row_mask:0xf bank_mask:0xf
	v_mov_b32_dpp v134, v124 row_ror:1 row_mask:0xf bank_mask:0xf
	v_mov_b32_dpp v136, v124 row_ror:2 row_mask:0xf bank_mask:0xf
	v_mov_b32_dpp v138, v125 row_ror:1 row_mask:0xf bank_mask:0xf
	v_mov_b32_dpp v140, v125 row_ror:2 row_mask:0xf bank_mask:0xf
	v_mov_b32_dpp v83, v56 row_shr:1 row_mask:0xf bank_mask:0xf
	v_pk_fma_f32 v[126:127], v[78:79], v[126:127], v[122:123]
	v_mov_b32_e32 v124, v110
	v_mov_b32_e32 v125, v84
	v_pk_fma_f32 v[82:83], v[124:125], v[82:83], v[126:127]
	v_mov_b32_e32 v142, v60
	v_mov_b32_e32 v143, v56
	v_mov_b32_e32 v126, v92
	v_mov_b32_e32 v127, v66
	v_mov_b32_dpp v131, v119 row_ror:2 row_mask:0xf bank_mask:0xf
	v_mov_b32_dpp v130, v61 row_shr:2 row_mask:0xf bank_mask:0xf
	v_pk_fma_f32 v[82:83], v[142:143], v[126:127], v[82:83]
	v_mov_b32_dpp v131, v57 row_shr:2 row_mask:0xf bank_mask:0xf
	v_mov_b32_e32 v74, v115
	v_mov_b32_e32 v70, v101
	v_pk_fma_f32 v[100:101], v[74:75], v[130:131], v[70:71]
	v_mov_b32_e32 v131, v68
	v_mul_f32_e32 v68, 0x3d372713, v82
	v_mov_b32_dpp v129, v119 row_ror:1 row_mask:0xf bank_mask:0xf
	v_mul_f32_e32 v68, v82, v68
	v_mov_b32_dpp v128, v61 row_shr:1 row_mask:0xf bank_mask:0xf
	v_mov_b32_dpp v129, v57 row_shr:1 row_mask:0xf bank_mask:0xf
	v_mov_b32_e32 v84, v111
	v_fma_f32 v68, v82, v68, v82
	v_pk_fma_f32 v[100:101], v[84:85], v[128:129], v[100:101]
	v_mov_b32_e32 v110, v61
	v_mov_b32_e32 v111, v57
	v_mov_b32_e32 v66, v93
	v_mul_f32_e32 v68, 0x3fcc422a, v68
	v_pk_fma_f32 v[92:93], v[110:111], v[66:67], v[100:101]
	v_mul_f32_e32 v68, 0xbfb8aa3b, v68
	v_exp_f32_e32 v91, v68
	v_mul_f32_e32 v68, 0x3d372713, v92
	v_mul_f32_e32 v68, v92, v68
	v_fma_f32 v68, v92, v68, v92
	v_mul_f32_e32 v68, 0x3fcc422a, v68
	v_mul_f32_e32 v68, 0xbfb8aa3b, v68
	v_mov_b32_e32 v130, v94
	v_exp_f32_e32 v94, v68
	v_mov_b32_dpp v137, v120 row_ror:2 row_mask:0xf bank_mask:0xf
	v_add_f32_e32 v91, 1.0, v91
	v_mov_b32_dpp v136, v62 row_shr:2 row_mask:0xf bank_mask:0xf
	v_mov_b32_dpp v135, v120 row_ror:1 row_mask:0xf bank_mask:0xf
	v_mov_b32_dpp v137, v58 row_shr:2 row_mask:0xf bank_mask:0xf
	v_mov_b32_e32 v114, v116
	v_mov_b32_e32 v115, v76
	v_mov_b32_e32 v118, v102
	v_mov_b32_e32 v119, v72
	v_mov_b32_dpp v141, v121 row_ror:2 row_mask:0xf bank_mask:0xf
	v_rcp_f32_e32 v91, v91
	v_add_f32_e32 v94, 1.0, v94
	v_mov_b32_dpp v134, v62 row_shr:1 row_mask:0xf bank_mask:0xf
	v_mov_b32_dpp v140, v63 row_shr:2 row_mask:0xf bank_mask:0xf
	v_mov_b32_dpp v135, v58 row_shr:1 row_mask:0xf bank_mask:0xf
	v_pk_fma_f32 v[100:101], v[114:115], v[136:137], v[118:119]
	v_mov_b32_e32 v128, v112
	v_mov_b32_e32 v129, v86
	v_mov_b32_dpp v139, v121 row_ror:1 row_mask:0xf bank_mask:0xf
	v_mov_b32_dpp v141, v59 row_shr:2 row_mask:0xf bank_mask:0xf
	v_mov_b32_e32 v76, v117
	v_mov_b32_e32 v72, v103
	v_rcp_f32_e32 v112, v94
	v_mov_b32_dpp v138, v63 row_shr:1 row_mask:0xf bank_mask:0xf
	v_pk_fma_f32 v[100:101], v[128:129], v[134:135], v[100:101]
	v_mov_b32_e32 v110, v62
	v_mov_b32_e32 v111, v58
	v_mov_b32_dpp v139, v59 row_shr:1 row_mask:0xf bank_mask:0xf
	v_pk_fma_f32 v[102:103], v[76:77], v[140:141], v[72:73]
	v_mov_b32_e32 v86, v113
	v_pk_fma_f32 v[100:101], v[110:111], v[130:131], v[100:101]
	v_pk_fma_f32 v[102:103], v[86:87], v[138:139], v[102:103]
	v_mov_b32_e32 v110, v63
	v_mov_b32_e32 v111, v59
	v_mov_b32_e32 v68, v95
	v_pk_fma_f32 v[94:95], v[110:111], v[68:69], v[102:103]
	v_mul_f32_e32 v82, v82, v91
	v_mul_f32_e32 v82, v82, v83
	v_mul_f32_e32 v83, v92, v112
	v_mul_f32_e32 v91, 0x3d372713, v100
	v_mul_f32_e32 v92, 0x3d372713, v94
	v_mul_f32_e32 v91, v100, v91
	v_mul_f32_e32 v92, v94, v92
	v_fma_f32 v91, v100, v91, v100
	v_fma_f32 v92, v94, v92, v94
	v_mul_f32_e32 v91, 0x3fcc422a, v91
	v_mul_f32_e32 v92, 0x3fcc422a, v92
	v_mul_f32_e32 v91, 0xbfb8aa3b, v91
	v_mul_f32_e32 v92, 0xbfb8aa3b, v92
	v_exp_f32_e32 v91, v91
	v_exp_f32_e32 v92, v92
	v_mul_f32_e32 v83, v83, v93
	s_lshl_b32 s3, s50, 8
	v_add_f32_e32 v91, 1.0, v91
	v_add_f32_e32 v92, 1.0, v92
	v_rcp_f32_e32 v91, v91
	v_rcp_f32_e32 v92, v92
	v_cvt_pk_bf16_f32 v110, v82, v83
	s_add_i32 s3, s3, s76
	v_mul_f32_e32 v82, v100, v91
	v_mul_f32_e32 v83, v94, v92
	v_mul_f32_e32 v82, v82, v101
	v_mul_f32_e32 v83, v83, v95
	v_or_b32_e32 v132, s3, v199
	v_cvt_pk_bf16_f32 v111, v82, v83
	v_mov_b64_e32 v[82:83], s[36:37]
	v_mad_i64_i32 v[92:93], s[8:9], v132, s94, v[82:83]
	v_lshlrev_b64 v[94:95], 1, v[186:187]
	v_lshl_add_u64 v[92:93], v[92:93], 0, v[94:95]
	global_store_dwordx4 v[92:93], v[108:111], off
	v_mov_b32_dpp v100, v60 row_ror:2 row_mask:0xf bank_mask:0xf
	v_mov_b32_dpp v101, v56 row_ror:2 row_mask:0xf bank_mask:0xf
	v_mov_b32_dpp v92, v60 row_ror:1 row_mask:0xf bank_mask:0xf
	v_mov_b32_dpp v100, v52 row_shr:2 row_mask:0xf bank_mask:0xf
	v_mov_b32_dpp v108, v62 row_ror:1 row_mask:0xf bank_mask:0xf
	v_mov_b32_dpp v110, v62 row_ror:2 row_mask:0xf bank_mask:0xf
	v_mov_b32_dpp v93, v56 row_ror:1 row_mask:0xf bank_mask:0xf
	v_mov_b32_dpp v101, v48 row_shr:2 row_mask:0xf bank_mask:0xf
; __device__ __forceinline__ unsigned cvt_pk_bf16(float lo, float hi) { unsigned r; asm volatile("v_cvt_pk_bf16_f32 %0, %1, %2" : "=v"(r) : "v"(lo), "v"(hi)); return r; }
; __device__ __forceinline__ float gelu_t(float x) { const float u = 1.5957691216f * (x + 0.044715f * x * x * x); return x * sigm(u); }
; __device__ __forceinline__ float dpp_shr1(float old, float src) { return __int_as_float(__builtin_amdgcn_update_dpp(__float_as_int(old), __float_as_int(src), 0x111, 0xf, 0xf, false)); }
; __device__ __forceinline__ float dpp_shr2(float old, float src) { return __int_as_float(__builtin_amdgcn_update_dpp(__float_as_int(old), __float_as_int(src), 0x112, 0xf, 0xf, false)); }
; __device__ __forceinline__ float dpp_ror1(float src) { return __int_as_float(__builtin_amdgcn_update_dpp(0, __float_as_int(src), 0x121, 0xf, 0xf, false)); }
; __device__ __forceinline__ float dpp_ror2(float src) { return __int_as_float(__builtin_amdgcn_update_dpp(0, __float_as_int(src), 0x122, 0xf, 0xf, false)); }
;     __device__ __forceinline__ void operator()(AccT& acc, const Unit& u, int wr, int wc, int fr, int fq) const {
;     ...
;                 for (int m = 0; m < 4; ++m) {
;                     f32x4 c2[2];
; #pragma unroll
;                     for (int bj = 0; bj < 2; ++bj) { const f32x4 cur = acc[ai][bj][m][n]; const f32x4 pv = (m == 0) ? hv[bj] : acc[ai][bj][m == 0 ? 0 : m - 1][n];
; #pragma unroll
;                         for (int j = 0; j < 4; ++j) { const float p1 = dpp_shr1(dpp_ror1(pv[j]), cur[j]), p2 = dpp_shr2(dpp_ror2(pv[j]), cur[j]);
;                             c2[bj][j] = bia[bj][j] + wgt[bj][0][j] * p2 + wgt[bj][1][j] * p1 + wgt[bj][2][j] * cur[j]; } }
;                     u32x2 w; w.x = cvt_pk_bf16(gelu_t(c2[0][0]) * c2[1][0], gelu_t(c2[0][1]) * c2[1][1]); w.y = cvt_pk_bf16(gelu_t(c2[0][2]) * c2[1][2], gelu_t(c2[0][3]) * c2[1][3]);
;                     if (n == 0) pend[ai][m] = w;
;                     else { u32x4 w4; w4.x = pend[ai][m].x; w4.y = pend[ai][m].y; w4.z = w.x; w4.w = w.y;
;                         *(u32x4*)(F + (size_t)(t0 + ai * 128 + wr * 64 + m * 16 + fr) * FF + cg - 4) = w4; }
	v_mov_b32_dpp v92, v52 row_shr:1 row_mask:0xf bank_mask:0xf
	v_mov_b32_dpp v62, v63 row_ror:1 row_mask:0xf bank_mask:0xf
	v_mov_b32_dpp v112, v63 row_ror:2 row_mask:0xf bank_mask:0xf
	v_mov_b32_dpp v93, v48 row_shr:1 row_mask:0xf bank_mask:0xf
	v_pk_fma_f32 v[100:101], v[78:79], v[100:101], v[122:123]
	v_mov_b32_dpp v113, v59 row_ror:2 row_mask:0xf bank_mask:0xf
	v_mov_b32_dpp v112, v55 row_shr:2 row_mask:0xf bank_mask:0xf
	v_pk_fma_f32 v[92:93], v[124:125], v[92:93], v[100:101]
	v_mov_b32_e32 v100, v52
	v_mov_b32_e32 v101, v48
	v_mov_b32_dpp v63, v59 row_ror:1 row_mask:0xf bank_mask:0xf
	v_mov_b32_dpp v113, v51 row_shr:2 row_mask:0xf bank_mask:0xf
	v_mov_b32_dpp v62, v55 row_shr:1 row_mask:0xf bank_mask:0xf
	v_pk_fma_f32 v[92:93], v[100:101], v[126:127], v[92:93]
	v_mov_b32_dpp v109, v58 row_ror:1 row_mask:0xf bank_mask:0xf
	v_mov_b32_dpp v111, v58 row_ror:2 row_mask:0xf bank_mask:0xf
	v_mov_b32_dpp v63, v51 row_shr:1 row_mask:0xf bank_mask:0xf
	v_pk_fma_f32 v[58:59], v[76:77], v[112:113], v[72:73]
	v_pk_fma_f32 v[58:59], v[86:87], v[62:63], v[58:59]
	v_mul_f32_e32 v63, 0x3d372713, v92
	v_mul_f32_e32 v63, v92, v63
	v_mov_b32_dpp v60, v61 row_ror:1 row_mask:0xf bank_mask:0xf
	v_mov_b32_dpp v102, v61 row_ror:2 row_mask:0xf bank_mask:0xf
	v_mov_b32_dpp v103, v57 row_ror:2 row_mask:0xf bank_mask:0xf
	v_fma_f32 v63, v92, v63, v92
	v_mov_b32_dpp v102, v53 row_shr:2 row_mask:0xf bank_mask:0xf
	v_mov_b32_dpp v61, v57 row_ror:1 row_mask:0xf bank_mask:0xf
	v_mov_b32_dpp v103, v49 row_shr:2 row_mask:0xf bank_mask:0xf
	v_mul_f32_e32 v63, 0x3fcc422a, v63
	v_mov_b32_dpp v60, v53 row_shr:1 row_mask:0xf bank_mask:0xf
	v_mov_b32_dpp v61, v49 row_shr:1 row_mask:0xf bank_mask:0xf
	v_pk_fma_f32 v[56:57], v[74:75], v[102:103], v[70:71]
	v_mul_f32_e32 v63, 0xbfb8aa3b, v63
	v_pk_fma_f32 v[56:57], v[84:85], v[60:61], v[56:57]
	v_mov_b32_e32 v60, v53
	v_mov_b32_e32 v61, v49
	v_exp_f32_e32 v91, v63
	v_pk_fma_f32 v[56:57], v[60:61], v[66:67], v[56:57]
	v_mov_b32_dpp v110, v54 row_shr:2 row_mask:0xf bank_mask:0xf
	v_mul_f32_e32 v63, 0x3d372713, v56
	v_mul_f32_e32 v63, v56, v63
	v_mov_b32_dpp v111, v50 row_shr:2 row_mask:0xf bank_mask:0xf
	v_fma_f32 v63, v56, v63, v56
	v_add_f32_e32 v91, 1.0, v91
	v_mov_b32_dpp v108, v54 row_shr:1 row_mask:0xf bank_mask:0xf
	v_mov_b32_dpp v109, v50 row_shr:1 row_mask:0xf bank_mask:0xf
	v_pk_fma_f32 v[60:61], v[114:115], v[110:111], v[118:119]
	v_mul_f32_e32 v63, 0x3fcc422a, v63
	v_rcp_f32_e32 v91, v91
	v_pk_fma_f32 v[60:61], v[128:129], v[108:109], v[60:61]
	v_mov_b32_e32 v100, v54
	v_mov_b32_e32 v101, v50
	v_mul_f32_e32 v63, 0xbfb8aa3b, v63
	v_pk_fma_f32 v[60:61], v[100:101], v[130:131], v[60:61]
	v_mov_b32_e32 v62, v55
	v_exp_f32_e32 v100, v63
	v_mov_b32_e32 v63, v51
	v_pk_fma_f32 v[58:59], v[62:63], v[68:69], v[58:59]
	v_mul_f32_e32 v63, 0x3d372713, v60
	v_mul_f32_e32 v62, v92, v91
	v_mul_f32_e32 v63, v60, v63
	v_mul_f32_e32 v91, 0x3d372713, v58
	v_fma_f32 v63, v60, v63, v60
	v_mul_f32_e32 v91, v58, v91
	v_add_f32_e32 v100, 1.0, v100
	v_mul_f32_e32 v63, 0x3fcc422a, v63
	v_fma_f32 v91, v58, v91, v58
	v_rcp_f32_e32 v100, v100
	v_mul_f32_e32 v63, 0xbfb8aa3b, v63
	v_mul_f32_e32 v91, 0x3fcc422a, v91
	v_exp_f32_e32 v63, v63
	v_mul_f32_e32 v91, 0xbfb8aa3b, v91
	v_exp_f32_e32 v91, v91
	v_mul_f32_e32 v56, v56, v100
	v_mul_f32_e32 v56, v56, v57
	v_add_f32_e32 v57, 1.0, v63
	v_rcp_f32_e32 v57, v57
	v_add_f32_e32 v63, 1.0, v91
	v_rcp_f32_e32 v63, v63
	v_mul_f32_e32 v62, v62, v93
	v_cvt_pk_bf16_f32 v108, v62, v56
	v_mul_f32_e32 v56, v60, v57
	v_mul_f32_e32 v56, v56, v61
	v_mul_f32_e32 v57, v58, v63
	v_mul_f32_e32 v57, v57, v59
	v_cvt_pk_bf16_f32 v109, v56, v57
	v_or_b32_e32 v56, 16, v132
	v_mad_i64_i32 v[56:57], s[8:9], v56, s94, v[82:83]
	v_lshl_add_u64 v[56:57], v[56:57], 0, v[94:95]
	global_store_dwordx4 v[56:57], v[106:109], off
	v_mov_b32_dpp v58, v52 row_ror:2 row_mask:0xf bank_mask:0xf
	v_mov_b32_dpp v59, v48 row_ror:2 row_mask:0xf bank_mask:0xf
	v_mov_b32_dpp v56, v52 row_ror:1 row_mask:0xf bank_mask:0xf
	v_mov_b32_dpp v58, v44 row_shr:2 row_mask:0xf bank_mask:0xf
	v_mov_b32_dpp v62, v54 row_ror:1 row_mask:0xf bank_mask:0xf
	v_mov_b32_dpp v92, v54 row_ror:2 row_mask:0xf bank_mask:0xf
	v_mov_b32_dpp v57, v48 row_ror:1 row_mask:0xf bank_mask:0xf
	v_mov_b32_dpp v59, v40 row_shr:2 row_mask:0xf bank_mask:0xf
	v_mov_b32_dpp v56, v44 row_shr:1 row_mask:0xf bank_mask:0xf
	v_mov_b32_dpp v54, v55 row_ror:1 row_mask:0xf bank_mask:0xf
	v_mov_b32_dpp v100, v55 row_ror:2 row_mask:0xf bank_mask:0xf
	v_mov_b32_dpp v57, v40 row_shr:1 row_mask:0xf bank_mask:0xf
	v_pk_fma_f32 v[58:59], v[78:79], v[58:59], v[122:123]
	v_mov_b32_dpp v101, v51 row_ror:2 row_mask:0xf bank_mask:0xf
	v_mov_b32_dpp v100, v47 row_shr:2 row_mask:0xf bank_mask:0xf
	v_pk_fma_f32 v[56:57], v[124:125], v[56:57], v[58:59]
	v_mov_b32_e32 v58, v44
	v_mov_b32_e32 v59, v40
	v_mov_b32_dpp v55, v51 row_ror:1 row_mask:0xf bank_mask:0xf
	v_mov_b32_dpp v101, v43 row_shr:2 row_mask:0xf bank_mask:0xf
	v_mov_b32_dpp v52, v53 row_ror:1 row_mask:0xf bank_mask:0xf
	v_mov_b32_dpp v60, v53 row_ror:2 row_mask:0xf bank_mask:0xf
	v_mov_b32_dpp v54, v47 row_shr:1 row_mask:0xf bank_mask:0xf
	v_pk_fma_f32 v[56:57], v[58:59], v[126:127], v[56:57]
	v_mov_b32_dpp v61, v49 row_ror:2 row_mask:0xf bank_mask:0xf
	v_mov_b32_dpp v63, v50 row_ror:1 row_mask:0xf bank_mask:0xf
	v_mov_b32_dpp v93, v50 row_ror:2 row_mask:0xf bank_mask:0xf
	v_mov_b32_dpp v55, v43 row_shr:1 row_mask:0xf bank_mask:0xf
	v_pk_fma_f32 v[50:51], v[76:77], v[100:101], v[72:73]
	v_mov_b32_dpp v60, v45 row_shr:2 row_mask:0xf bank_mask:0xf
	v_mov_b32_dpp v53, v49 row_ror:1 row_mask:0xf bank_mask:0xf
	v_mov_b32_dpp v61, v41 row_shr:2 row_mask:0xf bank_mask:0xf
; #define LAS __attribute__((address_space(3)))
; __device__ __forceinline__ unsigned cvt_pk_bf16(float lo, float hi) { unsigned r; asm volatile("v_cvt_pk_bf16_f32 %0, %1, %2" : "=v"(r) : "v"(lo), "v"(hi)); return r; }
; __device__ __forceinline__ float gelu_t(float x) { const float u = 1.5957691216f * (x + 0.044715f * x * x * x); return x * sigm(u); }
; __device__ __forceinline__ float dpp_shr1(float old, float src) { return __int_as_float(__builtin_amdgcn_update_dpp(__float_as_int(old), __float_as_int(src), 0x111, 0xf, 0xf, false)); }
; __device__ __forceinline__ float dpp_shr2(float old, float src) { return __int_as_float(__builtin_amdgcn_update_dpp(__float_as_int(old), __float_as_int(src), 0x112, 0xf, 0xf, false)); }
; __device__ __forceinline__ float dpp_ror1(float src) { return __int_as_float(__builtin_amdgcn_update_dpp(0, __float_as_int(src), 0x121, 0xf, 0xf, false)); }
; __device__ __forceinline__ float dpp_ror2(float src) { return __int_as_float(__builtin_amdgcn_update_dpp(0, __float_as_int(src), 0x122, 0xf, 0xf, false)); }
;     __device__ __forceinline__ void operator()(AccT& acc, const Unit& u, int wr, int wc, int fr, int fq) const {
;     ...
;                 if (has_pred && fr >= 14) { hv[0] = *(const LAS f32x4*)(xl + xidx(pa, pw, wc, fr - 14, fq, 0, n)); hv[1] = *(const LAS f32x4*)(xl + xidx(pa, pw, wc, fr - 14, fq, 1, n)); }
; #pragma unroll
;                 for (int m = 0; m < 4; ++m) {
;                     f32x4 c2[2];
; #pragma unroll
;                     for (int bj = 0; bj < 2; ++bj) { const f32x4 cur = acc[ai][bj][m][n]; const f32x4 pv = (m == 0) ? hv[bj] : acc[ai][bj][m == 0 ? 0 : m - 1][n];
; #pragma unroll
;                         for (int j = 0; j < 4; ++j) { const float p1 = dpp_shr1(dpp_ror1(pv[j]), cur[j]), p2 = dpp_shr2(dpp_ror2(pv[j]), cur[j]);
;                             c2[bj][j] = bia[bj][j] + wgt[bj][0][j] * p2 + wgt[bj][1][j] * p1 + wgt[bj][2][j] * cur[j]; } }
;                     u32x2 w; w.x = cvt_pk_bf16(gelu_t(c2[0][0]) * c2[1][0], gelu_t(c2[0][1]) * c2[1][1]); w.y = cvt_pk_bf16(gelu_t(c2[0][2]) * c2[1][2], gelu_t(c2[0][3]) * c2[1][3]);
;                     if (n == 0) pend[ai][m] = w;
;                     else { u32x4 w4; w4.x = pend[ai][m].x; w4.y = pend[ai][m].y; w4.z = w.x; w4.w = w.y;
;                         *(u32x4*)(F + (size_t)(t0 + ai * 128 + wr * 64 + m * 16 + fr) * FF + cg - 4) = w4; }
	v_pk_fma_f32 v[50:51], v[86:87], v[54:55], v[50:51]
	v_mul_f32_e32 v55, 0x3d372713, v56
	v_mov_b32_dpp v52, v45 row_shr:1 row_mask:0xf bank_mask:0xf
	v_mov_b32_dpp v53, v41 row_shr:1 row_mask:0xf bank_mask:0xf
	v_pk_fma_f32 v[48:49], v[74:75], v[60:61], v[70:71]
	v_mul_f32_e32 v55, v56, v55
	v_mov_b32_dpp v92, v46 row_shr:2 row_mask:0xf bank_mask:0xf
	v_pk_fma_f32 v[48:49], v[84:85], v[52:53], v[48:49]
	v_mov_b32_e32 v52, v45
	v_mov_b32_e32 v53, v41
	v_mov_b32_dpp v93, v42 row_shr:2 row_mask:0xf bank_mask:0xf
	v_fma_f32 v55, v56, v55, v56
	v_mov_b32_dpp v62, v46 row_shr:1 row_mask:0xf bank_mask:0xf
	v_pk_fma_f32 v[48:49], v[52:53], v[66:67], v[48:49]
	v_mov_b32_dpp v63, v42 row_shr:1 row_mask:0xf bank_mask:0xf
	v_pk_fma_f32 v[52:53], v[114:115], v[92:93], v[118:119]
	v_mul_f32_e32 v55, 0x3fcc422a, v55
	v_pk_fma_f32 v[52:53], v[128:129], v[62:63], v[52:53]
	v_mov_b32_e32 v58, v46
	v_mov_b32_e32 v59, v42
	v_mul_f32_e32 v55, 0xbfb8aa3b, v55
	v_pk_fma_f32 v[52:53], v[58:59], v[130:131], v[52:53]
	v_exp_f32_e32 v58, v55
	v_mul_f32_e32 v55, 0x3d372713, v48
	v_mul_f32_e32 v55, v48, v55
	v_fma_f32 v55, v48, v55, v48
	v_add_f32_e32 v58, 1.0, v58
	v_mul_f32_e32 v55, 0x3fcc422a, v55
	v_rcp_f32_e32 v58, v58
	v_mul_f32_e32 v55, 0xbfb8aa3b, v55
	v_mov_b32_e32 v54, v47
	v_exp_f32_e32 v59, v55
	v_mov_b32_e32 v55, v43
	v_pk_fma_f32 v[50:51], v[54:55], v[68:69], v[50:51]
	v_mul_f32_e32 v55, 0x3d372713, v52
	v_mul_f32_e32 v54, v56, v58
	v_mul_f32_e32 v55, v52, v55
	v_mul_f32_e32 v56, 0x3d372713, v50
	v_fma_f32 v55, v52, v55, v52
	v_mul_f32_e32 v56, v50, v56
	v_add_f32_e32 v59, 1.0, v59
	v_mul_f32_e32 v55, 0x3fcc422a, v55
	v_fma_f32 v56, v50, v56, v50
	v_rcp_f32_e32 v59, v59
	v_mul_f32_e32 v55, 0xbfb8aa3b, v55
	v_mul_f32_e32 v56, 0x3fcc422a, v56
	v_exp_f32_e32 v55, v55
	v_mul_f32_e32 v56, 0xbfb8aa3b, v56
	v_exp_f32_e32 v56, v56
	v_mul_f32_e32 v48, v48, v59
	v_mul_f32_e32 v48, v48, v49
	v_add_f32_e32 v49, 1.0, v55
	v_rcp_f32_e32 v49, v49
	v_add_f32_e32 v55, 1.0, v56
	v_rcp_f32_e32 v55, v55
	v_mul_f32_e32 v54, v54, v57
	v_cvt_pk_bf16_f32 v106, v54, v48
	v_mul_f32_e32 v48, v52, v49
	v_mul_f32_e32 v48, v48, v53
	v_mul_f32_e32 v49, v50, v55
	v_mul_f32_e32 v49, v49, v51
	v_cvt_pk_bf16_f32 v107, v48, v49
	v_or_b32_e32 v48, 32, v132
	v_mad_i64_i32 v[48:49], s[8:9], v48, s94, v[82:83]
	v_lshl_add_u64 v[48:49], v[48:49], 0, v[94:95]
	global_store_dwordx4 v[48:49], v[104:107], off
	v_mov_b32_dpp v48, v44 row_ror:1 row_mask:0xf bank_mask:0xf
	v_mov_b32_dpp v50, v44 row_ror:2 row_mask:0xf bank_mask:0xf
	v_mov_b32_dpp v51, v40 row_ror:2 row_mask:0xf bank_mask:0xf
	v_mov_b32_dpp v50, v36 row_shr:2 row_mask:0xf bank_mask:0xf
	v_mov_b32_dpp v44, v45 row_ror:1 row_mask:0xf bank_mask:0xf
	v_mov_b32_dpp v52, v45 row_ror:2 row_mask:0xf bank_mask:0xf
	v_mov_b32_dpp v49, v40 row_ror:1 row_mask:0xf bank_mask:0xf
	v_mov_b32_dpp v51, v32 row_shr:2 row_mask:0xf bank_mask:0xf
	v_mov_b32_dpp v53, v41 row_ror:2 row_mask:0xf bank_mask:0xf
	v_mov_b32_dpp v48, v36 row_shr:1 row_mask:0xf bank_mask:0xf
	v_mov_b32_dpp v52, v37 row_shr:2 row_mask:0xf bank_mask:0xf
	v_mov_b32_dpp v49, v32 row_shr:1 row_mask:0xf bank_mask:0xf
	v_pk_fma_f32 v[50:51], v[78:79], v[50:51], v[122:123]
	v_mov_b32_dpp v45, v41 row_ror:1 row_mask:0xf bank_mask:0xf
	v_mov_b32_dpp v53, v33 row_shr:2 row_mask:0xf bank_mask:0xf
	v_mov_b32_dpp v44, v37 row_shr:1 row_mask:0xf bank_mask:0xf
	v_pk_fma_f32 v[48:49], v[124:125], v[48:49], v[50:51]
	v_mov_b32_e32 v50, v36
	v_mov_b32_e32 v51, v32
	v_mov_b32_dpp v45, v33 row_shr:1 row_mask:0xf bank_mask:0xf
	v_pk_fma_f32 v[40:41], v[74:75], v[52:53], v[70:71]
	v_pk_fma_f32 v[48:49], v[50:51], v[126:127], v[48:49]
	v_pk_fma_f32 v[40:41], v[84:85], v[44:45], v[40:41]
	v_mov_b32_e32 v32, v37
	v_mov_b32_dpp v55, v42 row_ror:1 row_mask:0xf bank_mask:0xf
	v_mov_b32_dpp v57, v42 row_ror:2 row_mask:0xf bank_mask:0xf
	v_pk_fma_f32 v[32:33], v[32:33], v[66:67], v[40:41]
	v_mov_b32_dpp v55, v34 row_shr:1 row_mask:0xf bank_mask:0xf
	v_mov_b32_dpp v57, v34 row_shr:2 row_mask:0xf bank_mask:0xf
	v_mov_b32_e32 v41, v34
	v_mul_f32_e32 v34, 0x3d372713, v48
	v_mul_f32_e32 v34, v48, v34
	v_fma_f32 v34, v48, v34, v48
	v_mul_f32_e32 v34, 0x3fcc422a, v34
	v_mov_b32_dpp v54, v46 row_ror:1 row_mask:0xf bank_mask:0xf
	v_mov_b32_dpp v56, v46 row_ror:2 row_mask:0xf bank_mask:0xf
	v_mul_f32_e32 v34, 0xbfb8aa3b, v34
	v_mov_b32_dpp v54, v38 row_shr:1 row_mask:0xf bank_mask:0xf
	v_mov_b32_dpp v56, v38 row_shr:2 row_mask:0xf bank_mask:0xf
	v_mov_b32_e32 v40, v38
	v_exp_f32_e32 v38, v34
	v_mul_f32_e32 v34, 0x3d372713, v32
	v_mul_f32_e32 v34, v32, v34
	v_fma_f32 v34, v32, v34, v32
	v_mul_f32_e32 v34, 0x3fcc422a, v34
	v_mul_f32_e32 v34, 0xbfb8aa3b, v34
	v_exp_f32_e32 v42, v34
	v_mov_b32_dpp v46, v47 row_ror:1 row_mask:0xf bank_mask:0xf
	v_mov_b32_dpp v58, v47 row_ror:2 row_mask:0xf bank_mask:0xf
	v_mov_b32_e32 v34, v39
	v_mov_b32_dpp v46, v39 row_shr:1 row_mask:0xf bank_mask:0xf
	v_mov_b32_dpp v58, v39 row_shr:2 row_mask:0xf bank_mask:0xf
	v_add_f32_e32 v39, 1.0, v42
	v_pk_fma_f32 v[36:37], v[114:115], v[56:57], v[118:119]
	v_mov_b32_dpp v59, v43 row_ror:2 row_mask:0xf bank_mask:0xf
	v_rcp_f32_e32 v39, v39
	v_pk_fma_f32 v[36:37], v[128:129], v[54:55], v[36:37]
	v_mov_b32_dpp v47, v43 row_ror:1 row_mask:0xf bank_mask:0xf
	v_mov_b32_dpp v59, v35 row_shr:2 row_mask:0xf bank_mask:0xf
	v_pk_fma_f32 v[36:37], v[40:41], v[130:131], v[36:37]
	v_mov_b32_dpp v47, v35 row_shr:1 row_mask:0xf bank_mask:0xf
	v_pk_fma_f32 v[40:41], v[76:77], v[58:59], v[72:73]
	v_mul_f32_e32 v32, v32, v39
	v_pk_fma_f32 v[40:41], v[86:87], v[46:47], v[40:41]
	v_mul_f32_e32 v39, 0x3d372713, v36
	v_pk_fma_f32 v[34:35], v[34:35], v[68:69], v[40:41]
	v_mul_f32_e32 v39, v36, v39
	v_mul_f32_e32 v40, 0x3d372713, v34
	v_fma_f32 v39, v36, v39, v36
	v_mul_f32_e32 v40, v34, v40
	v_mul_f32_e32 v39, 0x3fcc422a, v39
	v_fma_f32 v40, v34, v40, v34
	v_mul_f32_e32 v39, 0xbfb8aa3b, v39
	v_mul_f32_e32 v40, 0x3fcc422a, v40
	v_exp_f32_e32 v39, v39
	v_mul_f32_e32 v40, 0xbfb8aa3b, v40
	v_exp_f32_e32 v40, v40
	v_add_f32_e32 v38, 1.0, v38
	v_rcp_f32_e32 v38, v38
	v_mul_f32_e32 v32, v32, v33
	v_add_f32_e32 v33, 1.0, v39
	v_rcp_f32_e32 v33, v33
	v_add_f32_e32 v39, 1.0, v40
	v_rcp_f32_e32 v39, v39
	v_mul_f32_e32 v38, v48, v38
	v_mul_f32_e32 v38, v38, v49
	v_cvt_pk_bf16_f32 v100, v38, v32
	v_mul_f32_e32 v32, v36, v33
	v_mul_f32_e32 v32, v32, v37
	v_mul_f32_e32 v33, v34, v39
	v_mul_f32_e32 v33, v33, v35
	v_cvt_pk_bf16_f32 v101, v32, v33
	v_or_b32_e32 v32, 48, v132
	v_mad_i64_i32 v[32:33], s[8:9], v32, s94, v[82:83]
	v_lshl_add_u64 v[32:33], v[32:33], 0, v[94:95]
	global_store_dwordx4 v[32:33], v[98:101], off
	v_mov_b32_e32 v91, 0
	v_mov_b32_e32 v92, 0
	v_mov_b32_e32 v93, 0
	v_mov_b32_e32 v32, 0
	v_mov_b32_e32 v33, 0
	v_mov_b32_e32 v34, 0
	v_mov_b32_e32 v35, 0
	s_and_saveexec_b64 s[12:13], s[6:7]
	s_cbranch_execz .LBB0_794
	ds_read_b128 v[32:35], v154 offset:16
	ds_read_b128 v[90:93], v154 offset:48
